# prep phase work rebalanced: Fourier-fold workgroups take no weight tiles and no modulation jobs; modulation sums as unrolled f32 FMAs; census loads batched (LayerNorm prefetch dropped)
# speedup vs baseline: 1.0096x; 1.0096x over previous
.LBB0_435:
	s_and_b64 vcc, exec, s[0:1]
	s_cbranch_vccz .LBB0_569
	s_mov_b32 s15, s45
	s_mov_b32 s14, 0
	s_add_i32 s26, s14, s76
	s_lshl_b64 s[0:1], s[14:15], 3
	s_add_u32 s0, s70, s0
	v_readlane_b32 s4, v253, 62
	s_addc_u32 s1, s71, s1
	v_readlane_b32 s6, v254, 0
	v_readlane_b32 s7, v254, 1
	s_add_u32 s2, s6, s14
	s_addc_u32 s3, s7, 0
	s_add_i32 s4, s14, s69
	s_add_i32 s36, s14, s72
	s_waitcnt vmcnt(0)
	v_mbcnt_lo_u32_b32 v36, -1, 0
	v_mbcnt_hi_u32_b32 v36, -1, v36
	s_mov_b32 s34, s4
	s_cmpk_gt_i32 s4, 0x163f
	v_lshl_add_u32 v176, s26, 6, v36
	v_readlane_b32 s5, v253, 63
	s_cbranch_scc1 .LBB0_488
	v_ashrrev_i32_e32 v2, 6, v176
	v_and_b32_e32 v3, 63, v36
	s_movk_i32 s4, 0x104
	v_mul_lo_u32 v0, v2, s4
	v_lshlrev_b32_e32 v1, 2, v3
	v_add3_u32 v4, 0, v0, v1
	v_lshlrev_b32_e32 v0, 3, v36
	s_waitcnt vmcnt(3)
	v_ashrrev_i32_e32 v18, 3, v176
	v_and_b32_e32 v0, 56, v0
	v_mul_u32_u24_e32 v1, 0x104, v0
	v_lshlrev_b32_e32 v19, 2, v18
	v_add_u32_e32 v5, 0x820, v4
	v_add_u32_e32 v6, 16, v2
	v_add_u32_e32 v7, 0x1040, v4
	v_add_u32_e32 v8, 24, v2
	v_add_u32_e32 v9, 0x1860, v4
	v_add_u32_e32 v10, 32, v2
	v_add_u32_e32 v11, 0x2080, v4
	v_add_u32_e32 v12, 40, v2
	v_add_u32_e32 v13, 0x28a0, v4
	v_add_u32_e32 v14, 48, v2
	v_add_u32_e32 v15, 0x30c0, v4
	v_add_u32_e32 v16, 56, v2
	v_add_u32_e32 v17, 0x38e0, v4
	v_add3_u32 v19, 0, v1, v19
	v_lshlrev_b32_e32 v192, 1, v0
	s_mov_b32 s15, s34
	s_mov_b32 s100, s36
	s_cmpk_lg_i32 s36, 0x100
	s_cbranch_scc1 .LBB0_439
	s_movk_i32 s100, 0xc0
	s_addk_i32 s15, 0xffc0
	s_cmp_lt_i32 s15, 0
	s_cbranch_scc1 .LBB0_488
	s_branch .LBB0_439
.LBB0_438:
	s_or_b64 exec, exec, s[4:5]
	s_waitcnt vmcnt(0)
	ds_write_b32 v17, v20
	s_waitcnt lgkmcnt(0)
	s_barrier
	ds_read2_b32 v[0:1], v19 offset1:65
	ds_read2_b32 v[22:23], v19 offset0:130 offset1:195
	v_add_u32_e32 v20, 0x400, v19
	ds_read2_b32 v[24:25], v20 offset0:4 offset1:69
	ds_read2_b32 v[26:27], v20 offset0:134 offset1:199
	s_add_u32 s4, s2, s6
	s_waitcnt lgkmcnt(3)
	v_cvt_pk_bf16_f32 v20, v0, v1
	v_add_u32_e32 v0, s21, v18
	s_addc_u32 s5, s3, s7
	s_waitcnt lgkmcnt(2)
	v_cvt_pk_bf16_f32 v21, v22, v23
	s_waitcnt lgkmcnt(1)
	v_cvt_pk_bf16_f32 v22, v24, v25
	v_ashrrev_i32_e32 v25, 31, v0
	v_mad_u64_u32 v[0:1], s[6:7], v0, s20, 0
	v_mov_b32_e32 v24, v1
	v_mad_u64_u32 v[24:25], s[6:7], v25, s20, v[24:25]
	v_mov_b32_e32 v1, v24
	v_lshl_add_u64 v[0:1], v[0:1], 1, s[4:5]
	s_ashr_i32 s13, s12, 31
	v_lshl_add_u64 v[0:1], s[12:13], 1, v[0:1]
	s_add_i32 s15, s15, s100
	s_waitcnt lgkmcnt(0)
	v_cvt_pk_bf16_f32 v23, v26, v27
	v_lshl_add_u64 v[0:1], v[0:1], 0, v[192:193]
	s_cmpk_gt_i32 s15, 0x163f
	global_store_dwordx4 v[0:1], v[20:23], off
	s_cbranch_scc1 .LBB0_488

.Lcvt_join:
	s_mov_b64 exec, s[18:19]
	s_mov_b64 s[4:5], exec
	s_waitcnt vmcnt(0)
	ds_write_b32 v4, v21
	ds_write_b32 v5, v22
	ds_write_b32 v7, v23
	ds_write_b32 v9, v24
	ds_write_b32 v11, v25
	ds_write_b32 v13, v26
	ds_write_b32 v15, v27
	s_branch .LBB0_438
	s_nop 0
	s_nop 0
	s_nop 0
	s_nop 0
	s_nop 0
	s_nop 0
	s_nop 0
	s_nop 0
	s_nop 0
	s_nop 0
	s_nop 0
	s_nop 0
	s_nop 0
	s_nop 0
.LBB0_486:
	s_mov_b64 s[6:7], 0x600000
	s_movk_i32 s23, 0x1600
	s_mov_b64 s[8:9], 0x1600
	s_cbranch_execz .LBB0_464
	s_branch .LBB0_465

.LBB0_548:
	s_or_b64 exec, exec, s[4:5]
	v_readlane_b32 s4, v254, 41
	s_cmpk_gt_i32 s4, 0x17f
	v_readlane_b32 s5, v254, 42
	s_cbranch_scc1 .LBB0_568
	s_waitcnt vmcnt(5)
	v_max_i32_e32 v8, 0xe80, v176
	s_load_dwordx2 s[10:11], s[0:1], 0x20
	v_lshlrev_b32_e32 v2, 2, v176
	v_sub_u32_e32 v8, v8, v176
	v_and_b32_e32 v192, 0x1fc, v2
	v_add_u32_e32 v8, 0x1ff, v8
	v_lshl_add_u64 v[6:7], s[2:3], 0, v[192:193]
	s_mov_b64 s[2:3], 0x3ea4000
	v_lshrrev_b32_e32 v9, 9, v8
	v_lshl_add_u64 v[6:7], v[6:7], 0, s[2:3]
	v_add_u32_e32 v9, 1, v9
	s_movk_i32 s2, 0x1ff
	s_movk_i32 s4, 0x2100
	v_ashrrev_i32_e32 v4, 7, v176
	v_cmp_lt_u32_e64 s[6:7], s2, v8
	s_waitcnt vmcnt(3)
	v_and_b32_e32 v49, 0xfffffe, v9
	v_lshlrev_b32_e32 v8, 2, v36
	v_cmp_gt_i32_e32 vcc, s4, v176
	v_lshl_add_u32 v3, v4, 8, 0
	v_add_u32_e32 v2, 0, v192
	s_movk_i32 s4, 0x4200
	v_cmp_ne_u32_e64 s[8:9], v9, v49
	v_lshl_add_u32 v10, s26, 8, v8
	s_waitcnt lgkmcnt(0)
	v_lshl_add_u64 v[8:9], s[10:11], 0, v[192:193]
	s_mov_b64 s[2:3], 0xc000
	v_lshlrev_b32_e32 v0, 6, v4
	v_mad_u64_u32 v[4:5], s[4:5], v4, s4, v[2:3]
	v_lshl_add_u64 v[8:9], v[8:9], 0, s[2:3]
	v_readlane_b32 s2, v254, 8
	s_movk_i32 s4, 0x1080
	v_ashrrev_i32_e32 v1, 31, v0
	s_waitcnt vmcnt(2)
	v_add_u32_e32 v53, s2, v10
	v_readlane_b32 s2, v254, 41
	v_cmp_gt_i32_e64 s[4:5], s4, v176
	v_and_b32_e32 v5, 0xff, v176
	v_lshl_add_u32 v51, v49, 9, v176
	v_mov_b32_e32 v177, v37
	v_add_u32_e32 v52, 0, v10
	s_mov_b32 s22, s2
	s_mov_b32 s23, s2
	v_readlane_b32 s3, v254, 42
	s_cmpk_lg_i32 s36, 0x100
	s_cbranch_scc1 .LBB0_551
	s_addk_i32 s22, 0xffc0
	s_mov_b32 s23, s22
	s_cmp_lt_i32 s22, 0
	s_cbranch_scc1 .LBB0_568
	s_branch .LBB0_551
.LBB0_550:
	s_or_b64 exec, exec, s[14:15]
	s_cmpk_lg_i32 s36, 0x100
	s_cbranch_scc1 .Lmodp_stride_g
	s_addk_i32 s23, 0xc0
	s_addk_i32 s22, 0xc0
	s_cmpk_gt_i32 s23, 0x17f
	s_cbranch_scc1 .LBB0_568
	s_branch .LBB0_551
	s_nop 0
	s_nop 0
	s_nop 0
	s_nop 0
	s_nop 0
	s_nop 0
	s_nop 0
	s_nop 0
	s_nop 0
